# P7 meta-row thin GEMM: inner loops process 5 k-blocks per trip with all 40 loads in flight (was 1 block per trip); on top of mnk order + saddr loads
# speedup vs baseline: 1.0046x; 1.0046x over previous
.Lthin_p70_g:
	s_add_i32 s100, s1, 5
	s_cmp_gt_i32 s100, s26
	s_cbranch_scc1 .Lthin_p70_t
	s_mov_b32 s98, s6
	s_ashr_i32 s99, s6, 31
	s_lshl_b64 s[98:99], s[98:99], 1
	v_lshl_add_u64 v[176:177], v[10:11], 0, s[98:99]
	v_lshl_add_u64 v[178:179], v[14:15], 0, s[98:99]
	global_load_dwordx4 v[44:47], v[176:177], off
	global_load_dwordx4 v[48:51], v[178:179], off
	global_load_dwordx4 v[52:55], v[176:177], off offset:16
	global_load_dwordx4 v[56:59], v[178:179], off offset:16
	global_load_dwordx4 v[60:63], v[176:177], off offset:32
	global_load_dwordx4 v[64:67], v[178:179], off offset:32
	global_load_dwordx4 v[68:71], v[176:177], off offset:48
	global_load_dwordx4 v[72:75], v[178:179], off offset:48
	global_load_dwordx4 v[76:79], v[176:177], off offset:256
	global_load_dwordx4 v[80:83], v[178:179], off offset:256
	global_load_dwordx4 v[84:87], v[176:177], off offset:272
	global_load_dwordx4 v[88:91], v[178:179], off offset:272
	global_load_dwordx4 v[92:95], v[176:177], off offset:288
	global_load_dwordx4 v[96:99], v[178:179], off offset:288
	global_load_dwordx4 v[100:103], v[176:177], off offset:304
	global_load_dwordx4 v[104:107], v[178:179], off offset:304
	global_load_dwordx4 v[108:111], v[176:177], off offset:512
	global_load_dwordx4 v[112:115], v[178:179], off offset:512
	global_load_dwordx4 v[116:119], v[176:177], off offset:528
	global_load_dwordx4 v[120:123], v[178:179], off offset:528
	global_load_dwordx4 v[124:127], v[176:177], off offset:544
	global_load_dwordx4 v[128:131], v[178:179], off offset:544
	global_load_dwordx4 v[132:135], v[176:177], off offset:560
	global_load_dwordx4 v[136:139], v[178:179], off offset:560
	global_load_dwordx4 v[140:143], v[176:177], off offset:768
	global_load_dwordx4 v[144:147], v[178:179], off offset:768
	global_load_dwordx4 v[148:151], v[176:177], off offset:784
	global_load_dwordx4 v[152:155], v[178:179], off offset:784
	global_load_dwordx4 v[156:159], v[176:177], off offset:800
	global_load_dwordx4 v[160:163], v[178:179], off offset:800
	global_load_dwordx4 v[164:167], v[176:177], off offset:816
	global_load_dwordx4 v[168:171], v[178:179], off offset:816
	global_load_dwordx4 v[188:191], v[176:177], off offset:1024
	global_load_dwordx4 v[192:195], v[178:179], off offset:1024
	global_load_dwordx4 v[196:199], v[176:177], off offset:1040
	global_load_dwordx4 v[200:203], v[178:179], off offset:1040
	global_load_dwordx4 v[204:207], v[176:177], off offset:1056
	global_load_dwordx4 v[208:211], v[178:179], off offset:1056
	global_load_dwordx4 v[212:215], v[176:177], off offset:1072
	global_load_dwordx4 v[216:219], v[178:179], off offset:1072
	s_add_i32 s1, s1, 5
	s_addk_i32 s6, 0x280
	s_waitcnt vmcnt(38)
	v_mfma_f32_16x16x32_bf16 v[2:5], v[44:47], v[48:51], v[2:5]
	s_waitcnt vmcnt(36)
	v_mfma_f32_16x16x32_bf16 v[2:5], v[52:55], v[56:59], v[2:5]
	s_waitcnt vmcnt(34)
	v_mfma_f32_16x16x32_bf16 v[2:5], v[60:63], v[64:67], v[2:5]
	s_waitcnt vmcnt(32)
	v_mfma_f32_16x16x32_bf16 v[2:5], v[68:71], v[72:75], v[2:5]
	s_waitcnt vmcnt(30)
	v_mfma_f32_16x16x32_bf16 v[2:5], v[76:79], v[80:83], v[2:5]
	s_waitcnt vmcnt(28)
	v_mfma_f32_16x16x32_bf16 v[2:5], v[84:87], v[88:91], v[2:5]
	s_waitcnt vmcnt(26)
	v_mfma_f32_16x16x32_bf16 v[2:5], v[92:95], v[96:99], v[2:5]
	s_waitcnt vmcnt(24)
	v_mfma_f32_16x16x32_bf16 v[2:5], v[100:103], v[104:107], v[2:5]
	s_waitcnt vmcnt(22)
	v_mfma_f32_16x16x32_bf16 v[2:5], v[108:111], v[112:115], v[2:5]
	s_waitcnt vmcnt(20)
	v_mfma_f32_16x16x32_bf16 v[2:5], v[116:119], v[120:123], v[2:5]
	s_waitcnt vmcnt(18)
	v_mfma_f32_16x16x32_bf16 v[2:5], v[124:127], v[128:131], v[2:5]
	s_waitcnt vmcnt(16)
	v_mfma_f32_16x16x32_bf16 v[2:5], v[132:135], v[136:139], v[2:5]
	s_waitcnt vmcnt(14)
	v_mfma_f32_16x16x32_bf16 v[2:5], v[140:143], v[144:147], v[2:5]
	s_waitcnt vmcnt(12)
	v_mfma_f32_16x16x32_bf16 v[2:5], v[148:151], v[152:155], v[2:5]
	s_waitcnt vmcnt(10)
	v_mfma_f32_16x16x32_bf16 v[2:5], v[156:159], v[160:163], v[2:5]
	s_waitcnt vmcnt(8)
	v_mfma_f32_16x16x32_bf16 v[2:5], v[164:167], v[168:171], v[2:5]
	s_waitcnt vmcnt(6)
	v_mfma_f32_16x16x32_bf16 v[2:5], v[188:191], v[192:195], v[2:5]
	s_waitcnt vmcnt(4)
	v_mfma_f32_16x16x32_bf16 v[2:5], v[196:199], v[200:203], v[2:5]
	s_waitcnt vmcnt(2)
	v_mfma_f32_16x16x32_bf16 v[2:5], v[204:207], v[208:211], v[2:5]
	s_waitcnt vmcnt(0)
	v_mfma_f32_16x16x32_bf16 v[2:5], v[212:215], v[216:219], v[2:5]
	s_branch .Lthin_p70_g
.Lthin_p70_t:
	s_cmp_ge_i32 s1, s26
	s_cbranch_scc1 .LBB0_2300

.Lthin_p71_g:
	s_add_i32 s100, s1, 5
	s_cmp_gt_i32 s100, s26
	s_cbranch_scc1 .Lthin_p71_t
	s_mov_b32 s98, s22
	s_ashr_i32 s99, s22, 31
	s_lshl_b64 s[98:99], s[98:99], 1
	v_lshl_add_u64 v[176:177], v[10:11], 0, s[98:99]
	v_lshl_add_u64 v[178:179], v[14:15], 0, s[98:99]
	global_load_dwordx4 v[44:47], v[176:177], off
	global_load_dwordx4 v[48:51], v[178:179], off
	global_load_dwordx4 v[52:55], v[176:177], off offset:16
	global_load_dwordx4 v[56:59], v[178:179], off offset:16
	global_load_dwordx4 v[60:63], v[176:177], off offset:32
	global_load_dwordx4 v[64:67], v[178:179], off offset:32
	global_load_dwordx4 v[68:71], v[176:177], off offset:48
	global_load_dwordx4 v[72:75], v[178:179], off offset:48
	global_load_dwordx4 v[76:79], v[176:177], off offset:256
	global_load_dwordx4 v[80:83], v[178:179], off offset:256
	global_load_dwordx4 v[84:87], v[176:177], off offset:272
	global_load_dwordx4 v[88:91], v[178:179], off offset:272
	global_load_dwordx4 v[92:95], v[176:177], off offset:288
	global_load_dwordx4 v[96:99], v[178:179], off offset:288
	global_load_dwordx4 v[100:103], v[176:177], off offset:304
	global_load_dwordx4 v[104:107], v[178:179], off offset:304
	global_load_dwordx4 v[108:111], v[176:177], off offset:512
	global_load_dwordx4 v[112:115], v[178:179], off offset:512
	global_load_dwordx4 v[116:119], v[176:177], off offset:528
	global_load_dwordx4 v[120:123], v[178:179], off offset:528
	global_load_dwordx4 v[124:127], v[176:177], off offset:544
	global_load_dwordx4 v[128:131], v[178:179], off offset:544
	global_load_dwordx4 v[132:135], v[176:177], off offset:560
	global_load_dwordx4 v[136:139], v[178:179], off offset:560
	global_load_dwordx4 v[140:143], v[176:177], off offset:768
	global_load_dwordx4 v[144:147], v[178:179], off offset:768
	global_load_dwordx4 v[148:151], v[176:177], off offset:784
	global_load_dwordx4 v[152:155], v[178:179], off offset:784
	global_load_dwordx4 v[156:159], v[176:177], off offset:800
	global_load_dwordx4 v[160:163], v[178:179], off offset:800
	global_load_dwordx4 v[164:167], v[176:177], off offset:816
	global_load_dwordx4 v[168:171], v[178:179], off offset:816
	global_load_dwordx4 v[188:191], v[176:177], off offset:1024
	global_load_dwordx4 v[192:195], v[178:179], off offset:1024
	global_load_dwordx4 v[196:199], v[176:177], off offset:1040
	global_load_dwordx4 v[200:203], v[178:179], off offset:1040
	global_load_dwordx4 v[204:207], v[176:177], off offset:1056
	global_load_dwordx4 v[208:211], v[178:179], off offset:1056
	global_load_dwordx4 v[212:215], v[176:177], off offset:1072
	global_load_dwordx4 v[216:219], v[178:179], off offset:1072
	s_add_i32 s1, s1, 5
	s_addk_i32 s22, 0x280
	s_waitcnt vmcnt(38)
	v_mfma_f32_16x16x32_bf16 v[2:5], v[44:47], v[48:51], v[2:5]
	s_waitcnt vmcnt(36)
	v_mfma_f32_16x16x32_bf16 v[2:5], v[52:55], v[56:59], v[2:5]
	s_waitcnt vmcnt(34)
	v_mfma_f32_16x16x32_bf16 v[2:5], v[60:63], v[64:67], v[2:5]
	s_waitcnt vmcnt(32)
	v_mfma_f32_16x16x32_bf16 v[2:5], v[68:71], v[72:75], v[2:5]
	s_waitcnt vmcnt(30)
	v_mfma_f32_16x16x32_bf16 v[2:5], v[76:79], v[80:83], v[2:5]
	s_waitcnt vmcnt(28)
	v_mfma_f32_16x16x32_bf16 v[2:5], v[84:87], v[88:91], v[2:5]
	s_waitcnt vmcnt(26)
	v_mfma_f32_16x16x32_bf16 v[2:5], v[92:95], v[96:99], v[2:5]
	s_waitcnt vmcnt(24)
	v_mfma_f32_16x16x32_bf16 v[2:5], v[100:103], v[104:107], v[2:5]
	s_waitcnt vmcnt(22)
	v_mfma_f32_16x16x32_bf16 v[2:5], v[108:111], v[112:115], v[2:5]
	s_waitcnt vmcnt(20)
	v_mfma_f32_16x16x32_bf16 v[2:5], v[116:119], v[120:123], v[2:5]
	s_waitcnt vmcnt(18)
	v_mfma_f32_16x16x32_bf16 v[2:5], v[124:127], v[128:131], v[2:5]
	s_waitcnt vmcnt(16)
	v_mfma_f32_16x16x32_bf16 v[2:5], v[132:135], v[136:139], v[2:5]
	s_waitcnt vmcnt(14)
	v_mfma_f32_16x16x32_bf16 v[2:5], v[140:143], v[144:147], v[2:5]
	s_waitcnt vmcnt(12)
	v_mfma_f32_16x16x32_bf16 v[2:5], v[148:151], v[152:155], v[2:5]
	s_waitcnt vmcnt(10)
	v_mfma_f32_16x16x32_bf16 v[2:5], v[156:159], v[160:163], v[2:5]
	s_waitcnt vmcnt(8)
	v_mfma_f32_16x16x32_bf16 v[2:5], v[164:167], v[168:171], v[2:5]
	s_waitcnt vmcnt(6)
	v_mfma_f32_16x16x32_bf16 v[2:5], v[188:191], v[192:195], v[2:5]
	s_waitcnt vmcnt(4)
	v_mfma_f32_16x16x32_bf16 v[2:5], v[196:199], v[200:203], v[2:5]
	s_waitcnt vmcnt(2)
	v_mfma_f32_16x16x32_bf16 v[2:5], v[204:207], v[208:211], v[2:5]
	s_waitcnt vmcnt(0)
	v_mfma_f32_16x16x32_bf16 v[2:5], v[212:215], v[216:219], v[2:5]
	s_branch .Lthin_p71_g
